# MFMA order: super-phase snake with m outer (12 srcB shares + 3 srcA shares), accumulator pairs adjacent
# speedup vs baseline: 1.0029x; 1.0029x over previous
.LBB0_32:
	s_add_u32 s28, s54, 0xfff80080
	s_addc_u32 s29, s55, -1
	s_add_i32 s30, 0, 0x10000
	s_cmp_eq_u32 s27, 28
	s_cselect_b32 s79, s13, s29
	s_cselect_b32 s78, s16, s28
	s_cselect_b32 s69, s9, s26
	s_cselect_b32 s68, s24, s25
	s_add_i32 s31, 0, 0x14000
	v_add_u32_e32 v142, s30, v184
	v_add_u32_e32 v172, s31, v184
	ds_read_b128 v[130:133], v142
	ds_read_b128 v[134:137], v142 offset:1024
	ds_read_b128 v[138:141], v142 offset:2048
	ds_read_b128 v[142:145], v142 offset:3072
	ds_read_b128 v[146:149], v172
	ds_read_b128 v[150:153], v172 offset:1024
	ds_read_b128 v[154:157], v172 offset:2048
	ds_read_b128 v[172:175], v172 offset:3072
	v_lshl_add_u64 v[212:213], s[54:55], 0, v[166:167]
	s_add_i32 m0, s42, 0xc000
	ds_read_b128 v[176:179], v186
	ds_read_b128 v[180:183], v186 offset:1024
	ds_read_b128 v[188:191], v186 offset:2048
	ds_read_b128 v[192:195], v186 offset:3072
	ds_read_b128 v[196:199], v186 offset:4096
	ds_read_b128 v[200:203], v186 offset:5120
	ds_read_b128 v[204:207], v186 offset:6144
	ds_read_b128 v[208:211], v186 offset:7168
	global_load_lds_dwordx4 v[212:213], off
	v_lshl_add_u64 v[212:213], s[54:55], 0, v[168:169]
	s_add_i32 m0, s42, 0xe000
	s_nop 0
	global_load_lds_dwordx4 v[212:213], off
	s_waitcnt vmcnt(8)
	s_waitcnt lgkmcnt(0)
	s_barrier
	s_setprio 1
	s_waitcnt lgkmcnt(0)
	v_mfma_f32_16x16x32_bf16 v[126:129], v[130:133], v[176:179], v[126:129]
	v_mfma_f32_16x16x32_bf16 v[126:129], v[134:137], v[180:183], v[126:129]
	v_mfma_f32_16x16x32_bf16 v[122:125], v[142:145], v[180:183], v[122:125]
	v_mfma_f32_16x16x32_bf16 v[122:125], v[138:141], v[176:179], v[122:125]
	v_mfma_f32_16x16x32_bf16 v[118:121], v[146:149], v[176:179], v[118:121]
	v_mfma_f32_16x16x32_bf16 v[118:121], v[150:153], v[180:183], v[118:121]
	v_mfma_f32_16x16x32_bf16 v[114:117], v[172:175], v[180:183], v[114:117]
	v_mfma_f32_16x16x32_bf16 v[114:117], v[154:157], v[176:179], v[114:117]
	v_mfma_f32_16x16x32_bf16 v[98:101], v[154:157], v[188:191], v[98:101]
	v_mfma_f32_16x16x32_bf16 v[98:101], v[172:175], v[192:195], v[98:101]
	v_mfma_f32_16x16x32_bf16 v[102:105], v[150:153], v[192:195], v[102:105]
	v_mfma_f32_16x16x32_bf16 v[102:105], v[146:149], v[188:191], v[102:105]
	v_mfma_f32_16x16x32_bf16 v[106:109], v[138:141], v[188:191], v[106:109]
	v_mfma_f32_16x16x32_bf16 v[106:109], v[142:145], v[192:195], v[106:109]
	v_mfma_f32_16x16x32_bf16 v[110:113], v[134:137], v[192:195], v[110:113]
	v_mfma_f32_16x16x32_bf16 v[110:113], v[130:133], v[188:191], v[110:113]
	s_setprio 0
	s_setprio 1
	v_mfma_f32_16x16x32_bf16 v[94:97], v[130:133], v[196:199], v[94:97]
	v_mfma_f32_16x16x32_bf16 v[94:97], v[134:137], v[200:203], v[94:97]
	v_mfma_f32_16x16x32_bf16 v[90:93], v[142:145], v[200:203], v[90:93]
	v_mfma_f32_16x16x32_bf16 v[90:93], v[138:141], v[196:199], v[90:93]
	v_mfma_f32_16x16x32_bf16 v[86:89], v[146:149], v[196:199], v[86:89]
	v_mfma_f32_16x16x32_bf16 v[86:89], v[150:153], v[200:203], v[86:89]
	v_mfma_f32_16x16x32_bf16 v[82:85], v[172:175], v[200:203], v[82:85]
	v_mfma_f32_16x16x32_bf16 v[82:85], v[154:157], v[196:199], v[82:85]
	v_mfma_f32_16x16x32_bf16 v[66:69], v[154:157], v[204:207], v[66:69]
	v_mfma_f32_16x16x32_bf16 v[66:69], v[172:175], v[208:211], v[66:69]
	v_mfma_f32_16x16x32_bf16 v[70:73], v[150:153], v[208:211], v[70:73]
	v_mfma_f32_16x16x32_bf16 v[70:73], v[146:149], v[204:207], v[70:73]
	v_mfma_f32_16x16x32_bf16 v[74:77], v[138:141], v[204:207], v[74:77]
	v_mfma_f32_16x16x32_bf16 v[74:77], v[142:145], v[208:211], v[74:77]
	v_mfma_f32_16x16x32_bf16 v[78:81], v[134:137], v[208:211], v[78:81]
	v_mfma_f32_16x16x32_bf16 v[78:81], v[130:133], v[204:207], v[78:81]
	s_setprio 0
	s_barrier
	s_add_i32 s28, s30, s11
	v_lshl_add_u64 v[212:213], s[68:69], 0, v[160:161]
	s_mov_b32 m0, s28
	ds_read_b128 v[176:179], v186 offset:16384
	ds_read_b128 v[180:183], v186 offset:17408
	ds_read_b128 v[188:191], v186 offset:18432
	ds_read_b128 v[192:195], v186 offset:19456
	ds_read_b128 v[196:199], v186 offset:20480
	ds_read_b128 v[200:203], v186 offset:21504
	ds_read_b128 v[204:207], v186 offset:22528
	ds_read_b128 v[208:211], v186 offset:23552
	global_load_lds_dwordx4 v[212:213], off
	s_add_i32 m0, s28, 0x2000
	s_add_u32 s28, s68, 0x80000
	v_lshl_add_u64 v[232:233], s[68:69], 0, v[164:165]
	s_addc_u32 s29, s69, 0
	s_add_i32 s30, s31, s11
	global_load_lds_dwordx4 v[232:233], off
	v_lshl_add_u64 v[234:235], s[28:29], 0, v[160:161]
	s_mov_b32 m0, s30
	v_lshl_add_u64 v[236:237], s[78:79], 0, v[162:163]
	global_load_lds_dwordx4 v[234:235], off
	v_lshl_add_u64 v[234:235], s[28:29], 0, v[164:165]
	s_add_i32 m0, s30, 0x2000
	s_nop 0
	global_load_lds_dwordx4 v[234:235], off
	v_lshl_add_u64 v[234:235], s[78:79], 0, v[158:159]
	s_mov_b32 m0, s42
	s_nop 0
	global_load_lds_dwordx4 v[234:235], off
	s_mov_b32 m0, s57
	s_nop 0
	global_load_lds_dwordx4 v[236:237], off
	s_waitcnt vmcnt(8)
	s_waitcnt lgkmcnt(0)
	s_barrier
	s_setprio 1
	s_waitcnt lgkmcnt(0)
	v_mfma_f32_16x16x32_bf16 v[62:65], v[130:133], v[176:179], v[62:65]
	v_mfma_f32_16x16x32_bf16 v[62:65], v[134:137], v[180:183], v[62:65]
	v_mfma_f32_16x16x32_bf16 v[58:61], v[142:145], v[180:183], v[58:61]
	v_mfma_f32_16x16x32_bf16 v[58:61], v[138:141], v[176:179], v[58:61]
	v_mfma_f32_16x16x32_bf16 v[54:57], v[146:149], v[176:179], v[54:57]
	v_mfma_f32_16x16x32_bf16 v[54:57], v[150:153], v[180:183], v[54:57]
	v_mfma_f32_16x16x32_bf16 v[50:53], v[172:175], v[180:183], v[50:53]
	v_mfma_f32_16x16x32_bf16 v[50:53], v[154:157], v[176:179], v[50:53]
	v_mfma_f32_16x16x32_bf16 v[34:37], v[154:157], v[188:191], v[34:37]
	v_mfma_f32_16x16x32_bf16 v[34:37], v[172:175], v[192:195], v[34:37]
	v_mfma_f32_16x16x32_bf16 v[38:41], v[150:153], v[192:195], v[38:41]
	v_mfma_f32_16x16x32_bf16 v[38:41], v[146:149], v[188:191], v[38:41]
	v_mfma_f32_16x16x32_bf16 v[42:45], v[138:141], v[188:191], v[42:45]
	v_mfma_f32_16x16x32_bf16 v[42:45], v[142:145], v[192:195], v[42:45]
	v_mfma_f32_16x16x32_bf16 v[46:49], v[134:137], v[192:195], v[46:49]
	v_mfma_f32_16x16x32_bf16 v[46:49], v[130:133], v[188:191], v[46:49]
	s_setprio 0
	s_setprio 1
	v_mfma_f32_16x16x32_bf16 v[30:33], v[130:133], v[196:199], v[30:33]
	v_mfma_f32_16x16x32_bf16 v[30:33], v[134:137], v[200:203], v[30:33]
	v_mfma_f32_16x16x32_bf16 v[26:29], v[142:145], v[200:203], v[26:29]
	v_mfma_f32_16x16x32_bf16 v[26:29], v[138:141], v[196:199], v[26:29]
	v_mfma_f32_16x16x32_bf16 v[22:25], v[146:149], v[196:199], v[22:25]
	v_mfma_f32_16x16x32_bf16 v[22:25], v[150:153], v[200:203], v[22:25]
	v_mfma_f32_16x16x32_bf16 v[18:21], v[172:175], v[200:203], v[18:21]
	v_mfma_f32_16x16x32_bf16 v[18:21], v[154:157], v[196:199], v[18:21]
	v_mfma_f32_16x16x32_bf16 v[2:5], v[154:157], v[204:207], v[2:5]
	v_mfma_f32_16x16x32_bf16 v[2:5], v[172:175], v[208:211], v[2:5]
	v_mfma_f32_16x16x32_bf16 v[6:9], v[150:153], v[208:211], v[6:9]
	v_mfma_f32_16x16x32_bf16 v[6:9], v[146:149], v[204:207], v[6:9]
	v_mfma_f32_16x16x32_bf16 v[10:13], v[138:141], v[204:207], v[10:13]
	v_mfma_f32_16x16x32_bf16 v[10:13], v[142:145], v[208:211], v[10:13]
	v_mfma_f32_16x16x32_bf16 v[14:17], v[134:137], v[208:211], v[14:17]
	v_mfma_f32_16x16x32_bf16 v[14:17], v[130:133], v[204:207], v[14:17]
	s_setprio 0
	s_barrier
	s_add_i32 s30, 0, 0x18000
	s_add_i32 s31, 0, 0x1c000
	v_add_u32_e32 v142, s30, v184
	v_add_u32_e32 v172, s31, v184
	ds_read_b128 v[130:133], v142
	ds_read_b128 v[134:137], v142 offset:1024
	ds_read_b128 v[138:141], v142 offset:2048
	ds_read_b128 v[142:145], v142 offset:3072
	ds_read_b128 v[146:149], v172
	ds_read_b128 v[150:153], v172 offset:1024
	ds_read_b128 v[154:157], v172 offset:2048
	ds_read_b128 v[172:175], v172 offset:3072
	s_add_u32 s28, s78, 0x80000
	s_addc_u32 s29, s79, 0
	s_mov_b32 m0, s67
	v_lshl_add_u64 v[238:239], s[28:29], 0, v[158:159]
	ds_read_b128 v[176:179], v186 offset:32768
	ds_read_b128 v[180:183], v186 offset:33792
	ds_read_b128 v[188:191], v186 offset:34816
	ds_read_b128 v[192:195], v186 offset:35840
	ds_read_b128 v[196:199], v186 offset:36864
	ds_read_b128 v[200:203], v186 offset:37888
	ds_read_b128 v[204:207], v186 offset:38912
	ds_read_b128 v[208:211], v186 offset:39936
	global_load_lds_dwordx4 v[238:239], off
	v_lshl_add_u64 v[238:239], s[28:29], 0, v[162:163]
	s_mov_b32 m0, s72
	s_nop 0
	global_load_lds_dwordx4 v[238:239], off
	s_waitcnt vmcnt(8)
	s_waitcnt lgkmcnt(0)
	s_barrier
	s_setprio 1
	s_waitcnt lgkmcnt(0)
	v_mfma_f32_16x16x32_bf16 v[126:129], v[130:133], v[176:179], v[126:129]
	v_mfma_f32_16x16x32_bf16 v[126:129], v[134:137], v[180:183], v[126:129]
	v_mfma_f32_16x16x32_bf16 v[122:125], v[142:145], v[180:183], v[122:125]
	v_mfma_f32_16x16x32_bf16 v[122:125], v[138:141], v[176:179], v[122:125]
	v_mfma_f32_16x16x32_bf16 v[118:121], v[146:149], v[176:179], v[118:121]
	v_mfma_f32_16x16x32_bf16 v[118:121], v[150:153], v[180:183], v[118:121]
	v_mfma_f32_16x16x32_bf16 v[114:117], v[172:175], v[180:183], v[114:117]
	v_mfma_f32_16x16x32_bf16 v[114:117], v[154:157], v[176:179], v[114:117]
	v_mfma_f32_16x16x32_bf16 v[98:101], v[154:157], v[188:191], v[98:101]
	v_mfma_f32_16x16x32_bf16 v[98:101], v[172:175], v[192:195], v[98:101]
	v_mfma_f32_16x16x32_bf16 v[102:105], v[150:153], v[192:195], v[102:105]
	v_mfma_f32_16x16x32_bf16 v[102:105], v[146:149], v[188:191], v[102:105]
	v_mfma_f32_16x16x32_bf16 v[106:109], v[138:141], v[188:191], v[106:109]
	v_mfma_f32_16x16x32_bf16 v[106:109], v[142:145], v[192:195], v[106:109]
	v_mfma_f32_16x16x32_bf16 v[110:113], v[134:137], v[192:195], v[110:113]
	v_mfma_f32_16x16x32_bf16 v[110:113], v[130:133], v[188:191], v[110:113]
	s_setprio 0
	s_setprio 1
	v_mfma_f32_16x16x32_bf16 v[94:97], v[130:133], v[196:199], v[94:97]
	v_mfma_f32_16x16x32_bf16 v[94:97], v[134:137], v[200:203], v[94:97]
	v_mfma_f32_16x16x32_bf16 v[90:93], v[142:145], v[200:203], v[90:93]
	v_mfma_f32_16x16x32_bf16 v[90:93], v[138:141], v[196:199], v[90:93]
	v_mfma_f32_16x16x32_bf16 v[86:89], v[146:149], v[196:199], v[86:89]
	v_mfma_f32_16x16x32_bf16 v[86:89], v[150:153], v[200:203], v[86:89]
	v_mfma_f32_16x16x32_bf16 v[82:85], v[172:175], v[200:203], v[82:85]
	v_mfma_f32_16x16x32_bf16 v[82:85], v[154:157], v[196:199], v[82:85]
	v_mfma_f32_16x16x32_bf16 v[66:69], v[154:157], v[204:207], v[66:69]
	v_mfma_f32_16x16x32_bf16 v[66:69], v[172:175], v[208:211], v[66:69]
	v_mfma_f32_16x16x32_bf16 v[70:73], v[150:153], v[208:211], v[70:73]
	v_mfma_f32_16x16x32_bf16 v[70:73], v[146:149], v[204:207], v[70:73]
	v_mfma_f32_16x16x32_bf16 v[74:77], v[138:141], v[204:207], v[74:77]
	v_mfma_f32_16x16x32_bf16 v[74:77], v[142:145], v[208:211], v[74:77]
	v_mfma_f32_16x16x32_bf16 v[78:81], v[134:137], v[208:211], v[78:81]
	v_mfma_f32_16x16x32_bf16 v[78:81], v[130:133], v[204:207], v[78:81]
	s_setprio 0
	s_barrier
	s_add_i32 s28, s30, s11
	v_lshl_add_u64 v[212:213], v[212:213], 0, s[62:63]
	s_mov_b32 m0, s28
	ds_read_b128 v[176:179], v186 offset:49152
	ds_read_b128 v[180:183], v186 offset:50176
	ds_read_b128 v[188:191], v186 offset:51200
	ds_read_b128 v[192:195], v186 offset:52224
	ds_read_b128 v[196:199], v186 offset:53248
	ds_read_b128 v[200:203], v186 offset:54272
	ds_read_b128 v[204:207], v186 offset:55296
	ds_read_b128 v[208:211], v186 offset:56320
	global_load_lds_dwordx4 v[212:213], off
	s_add_i32 m0, s28, 0x2000
	s_add_u32 s28, s68, 0x80080
	v_lshl_add_u64 v[212:213], v[232:233], 0, s[62:63]
	s_addc_u32 s29, s69, 0
	s_add_i32 s30, s31, s11
	global_load_lds_dwordx4 v[212:213], off
	v_lshl_add_u64 v[212:213], s[28:29], 0, v[160:161]
	s_mov_b32 m0, s30
	s_nop 0
	global_load_lds_dwordx4 v[212:213], off
	v_lshl_add_u64 v[212:213], s[28:29], 0, v[164:165]
	s_add_i32 m0, s30, 0x2000
	s_nop 0
	global_load_lds_dwordx4 v[212:213], off
	v_lshl_add_u64 v[212:213], v[234:235], 0, s[62:63]
	s_mov_b32 m0, s18
	s_nop 0
	global_load_lds_dwordx4 v[212:213], off
	v_lshl_add_u64 v[212:213], v[236:237], 0, s[62:63]
	s_mov_b32 m0, s19
	s_nop 0
	global_load_lds_dwordx4 v[212:213], off
	s_waitcnt vmcnt(8)
	s_waitcnt lgkmcnt(0)
	s_barrier
	s_setprio 1
	s_waitcnt lgkmcnt(0)
	v_mfma_f32_16x16x32_bf16 v[62:65], v[130:133], v[176:179], v[62:65]
	v_mfma_f32_16x16x32_bf16 v[62:65], v[134:137], v[180:183], v[62:65]
	v_mfma_f32_16x16x32_bf16 v[58:61], v[142:145], v[180:183], v[58:61]
	v_mfma_f32_16x16x32_bf16 v[58:61], v[138:141], v[176:179], v[58:61]
	v_mfma_f32_16x16x32_bf16 v[54:57], v[146:149], v[176:179], v[54:57]
	v_mfma_f32_16x16x32_bf16 v[54:57], v[150:153], v[180:183], v[54:57]
	v_mfma_f32_16x16x32_bf16 v[50:53], v[172:175], v[180:183], v[50:53]
	v_mfma_f32_16x16x32_bf16 v[50:53], v[154:157], v[176:179], v[50:53]
	v_mfma_f32_16x16x32_bf16 v[34:37], v[154:157], v[188:191], v[34:37]
	v_mfma_f32_16x16x32_bf16 v[34:37], v[172:175], v[192:195], v[34:37]
	v_mfma_f32_16x16x32_bf16 v[38:41], v[150:153], v[192:195], v[38:41]
	v_mfma_f32_16x16x32_bf16 v[38:41], v[146:149], v[188:191], v[38:41]
	v_mfma_f32_16x16x32_bf16 v[42:45], v[138:141], v[188:191], v[42:45]
	v_mfma_f32_16x16x32_bf16 v[42:45], v[142:145], v[192:195], v[42:45]
	v_mfma_f32_16x16x32_bf16 v[46:49], v[134:137], v[192:195], v[46:49]
	v_mfma_f32_16x16x32_bf16 v[46:49], v[130:133], v[188:191], v[46:49]
	s_setprio 0
	s_setprio 1
	v_mfma_f32_16x16x32_bf16 v[30:33], v[130:133], v[196:199], v[30:33]
	v_mfma_f32_16x16x32_bf16 v[30:33], v[134:137], v[200:203], v[30:33]
	v_mfma_f32_16x16x32_bf16 v[26:29], v[142:145], v[200:203], v[26:29]
	v_mfma_f32_16x16x32_bf16 v[26:29], v[138:141], v[196:199], v[26:29]
	v_mfma_f32_16x16x32_bf16 v[22:25], v[146:149], v[196:199], v[22:25]
	v_mfma_f32_16x16x32_bf16 v[22:25], v[150:153], v[200:203], v[22:25]
	v_mfma_f32_16x16x32_bf16 v[18:21], v[172:175], v[200:203], v[18:21]
	v_mfma_f32_16x16x32_bf16 v[18:21], v[154:157], v[196:199], v[18:21]
	v_mfma_f32_16x16x32_bf16 v[2:5], v[154:157], v[204:207], v[2:5]
	v_mfma_f32_16x16x32_bf16 v[2:5], v[172:175], v[208:211], v[2:5]
	v_mfma_f32_16x16x32_bf16 v[6:9], v[150:153], v[208:211], v[6:9]
	v_mfma_f32_16x16x32_bf16 v[6:9], v[146:149], v[204:207], v[6:9]
	v_mfma_f32_16x16x32_bf16 v[10:13], v[138:141], v[204:207], v[10:13]
	v_mfma_f32_16x16x32_bf16 v[10:13], v[142:145], v[208:211], v[10:13]
	v_mfma_f32_16x16x32_bf16 v[14:17], v[134:137], v[208:211], v[14:17]
	v_mfma_f32_16x16x32_bf16 v[14:17], v[130:133], v[204:207], v[14:17]
	s_setprio 0
	s_barrier
	s_add_i32 s27, s27, 2
	s_add_u32 s54, s54, 0x100
	s_addc_u32 s55, s55, 0
	s_add_u32 s25, s25, 0x100
	s_addc_u32 s26, s26, 0
	s_cmp_gt_u32 s27, 29
	s_cbranch_scc0 .LBB0_32
	s_and_b64 vcc, exec, s[2:3]
	s_cbranch_vccz .LBB0_35
	s_barrier

.LBB0_132:
	s_add_u32 s23, s48, 0xfff80080
	s_addc_u32 s24, s49, -1
	s_add_i32 s25, 0, 0x10000
	s_cmp_eq_u32 s22, 28
	s_cselect_b32 s69, s3, s24
	s_cselect_b32 s68, s18, s23
	s_cselect_b32 s51, s1, s21
	s_cselect_b32 s50, s19, s20
	s_add_i32 s23, 0, 0x14000
	v_add_u32_e32 v156, s25, v165
	v_add_u32_e32 v169, s23, v165
	ds_read_b128 v[144:147], v156
	ds_read_b128 v[148:151], v156 offset:1024
	ds_read_b128 v[152:155], v156 offset:2048
	ds_read_b128 v[156:159], v156 offset:3072
	ds_read_b128 v[160:163], v169
	ds_read_b128 v[170:173], v169 offset:1024
	ds_read_b128 v[174:177], v169 offset:2048
	ds_read_b128 v[178:181], v169 offset:3072
	v_lshl_add_u64 v[232:233], s[48:49], 0, v[140:141]
	s_add_i32 m0, s45, 0xc000
	ds_read_b128 v[182:185], v168
	ds_read_b128 v[186:189], v168 offset:1024
	ds_read_b128 v[190:193], v168 offset:2048
	ds_read_b128 v[194:197], v168 offset:3072
	ds_read_b128 v[198:201], v168 offset:4096
	ds_read_b128 v[202:205], v168 offset:5120
	ds_read_b128 v[206:209], v168 offset:6144
	ds_read_b128 v[210:213], v168 offset:7168
	global_load_lds_dwordx4 v[232:233], off
	v_lshl_add_u64 v[232:233], s[48:49], 0, v[142:143]
	s_add_i32 m0, s45, 0xe000
	s_nop 0
	global_load_lds_dwordx4 v[232:233], off
	s_waitcnt vmcnt(8)
	s_waitcnt lgkmcnt(0)
	s_barrier
	s_setprio 1
	s_waitcnt lgkmcnt(0)
	v_mfma_f32_16x16x32_bf16 v[126:129], v[144:147], v[182:185], v[126:129]
	v_mfma_f32_16x16x32_bf16 v[126:129], v[148:151], v[186:189], v[126:129]
	v_mfma_f32_16x16x32_bf16 v[122:125], v[156:159], v[186:189], v[122:125]
	v_mfma_f32_16x16x32_bf16 v[122:125], v[152:155], v[182:185], v[122:125]
	v_mfma_f32_16x16x32_bf16 v[118:121], v[160:163], v[182:185], v[118:121]
	v_mfma_f32_16x16x32_bf16 v[118:121], v[170:173], v[186:189], v[118:121]
	v_mfma_f32_16x16x32_bf16 v[114:117], v[178:181], v[186:189], v[114:117]
	v_mfma_f32_16x16x32_bf16 v[114:117], v[174:177], v[182:185], v[114:117]
	v_mfma_f32_16x16x32_bf16 v[90:93], v[174:177], v[190:193], v[90:93]
	v_mfma_f32_16x16x32_bf16 v[90:93], v[178:181], v[194:197], v[90:93]
	v_mfma_f32_16x16x32_bf16 v[98:101], v[170:173], v[194:197], v[98:101]
	v_mfma_f32_16x16x32_bf16 v[98:101], v[160:163], v[190:193], v[98:101]
	v_mfma_f32_16x16x32_bf16 v[106:109], v[152:155], v[190:193], v[106:109]
	v_mfma_f32_16x16x32_bf16 v[106:109], v[156:159], v[194:197], v[106:109]
	v_mfma_f32_16x16x32_bf16 v[110:113], v[148:151], v[194:197], v[110:113]
	v_mfma_f32_16x16x32_bf16 v[110:113], v[144:147], v[190:193], v[110:113]
	s_setprio 0
	s_setprio 1
	v_mfma_f32_16x16x32_bf16 v[102:105], v[144:147], v[198:201], v[102:105]
	v_mfma_f32_16x16x32_bf16 v[102:105], v[148:151], v[202:205], v[102:105]
	v_mfma_f32_16x16x32_bf16 v[94:97], v[156:159], v[202:205], v[94:97]
	v_mfma_f32_16x16x32_bf16 v[94:97], v[152:155], v[198:201], v[94:97]
	v_mfma_f32_16x16x32_bf16 v[82:85], v[160:163], v[198:201], v[82:85]
	v_mfma_f32_16x16x32_bf16 v[82:85], v[170:173], v[202:205], v[82:85]
	v_mfma_f32_16x16x32_bf16 v[74:77], v[178:181], v[202:205], v[74:77]
	v_mfma_f32_16x16x32_bf16 v[74:77], v[174:177], v[198:201], v[74:77]
	v_mfma_f32_16x16x32_bf16 v[66:69], v[174:177], v[206:209], v[66:69]
	v_mfma_f32_16x16x32_bf16 v[66:69], v[178:181], v[210:213], v[66:69]
	v_mfma_f32_16x16x32_bf16 v[70:73], v[170:173], v[210:213], v[70:73]
	v_mfma_f32_16x16x32_bf16 v[70:73], v[160:163], v[206:209], v[70:73]
	v_mfma_f32_16x16x32_bf16 v[78:81], v[152:155], v[206:209], v[78:81]
	v_mfma_f32_16x16x32_bf16 v[78:81], v[156:159], v[210:213], v[78:81]
	v_mfma_f32_16x16x32_bf16 v[86:89], v[148:151], v[210:213], v[86:89]
	v_mfma_f32_16x16x32_bf16 v[86:89], v[144:147], v[206:209], v[86:89]
	s_setprio 0
	s_barrier
	s_add_i32 s24, s25, s16
	v_lshl_add_u64 v[232:233], s[50:51], 0, v[132:133]
	s_mov_b32 m0, s24
	ds_read_b128 v[182:185], v168 offset:16384
	ds_read_b128 v[186:189], v168 offset:17408
	ds_read_b128 v[190:193], v168 offset:18432
	ds_read_b128 v[194:197], v168 offset:19456
	ds_read_b128 v[198:201], v168 offset:20480
	ds_read_b128 v[202:205], v168 offset:21504
	ds_read_b128 v[206:209], v168 offset:22528
	ds_read_b128 v[210:213], v168 offset:23552
	global_load_lds_dwordx4 v[232:233], off
	s_add_i32 m0, s24, 0x2000
	s_add_u32 s24, s50, 0x80000
	v_lshl_add_u64 v[234:235], s[50:51], 0, v[136:137]
	s_addc_u32 s25, s51, 0
	s_add_i32 s23, s23, s16
	global_load_lds_dwordx4 v[234:235], off
	v_lshl_add_u64 v[236:237], s[24:25], 0, v[132:133]
	s_mov_b32 m0, s23
	v_lshl_add_u64 v[238:239], s[68:69], 0, v[134:135]
	global_load_lds_dwordx4 v[236:237], off
	v_lshl_add_u64 v[236:237], s[24:25], 0, v[136:137]
	s_add_i32 m0, s23, 0x2000
	s_nop 0
	global_load_lds_dwordx4 v[236:237], off
	v_lshl_add_u64 v[236:237], s[68:69], 0, v[130:131]
	s_mov_b32 m0, s45
	s_nop 0
	global_load_lds_dwordx4 v[236:237], off
	s_mov_b32 m0, s57
	s_nop 0
	global_load_lds_dwordx4 v[238:239], off
	s_waitcnt vmcnt(8)
	s_waitcnt lgkmcnt(0)
	s_barrier
	s_setprio 1
	s_waitcnt lgkmcnt(0)
	v_mfma_f32_16x16x32_bf16 v[62:65], v[144:147], v[182:185], v[62:65]
	v_mfma_f32_16x16x32_bf16 v[62:65], v[148:151], v[186:189], v[62:65]
	v_mfma_f32_16x16x32_bf16 v[58:61], v[156:159], v[186:189], v[58:61]
	v_mfma_f32_16x16x32_bf16 v[58:61], v[152:155], v[182:185], v[58:61]
	v_mfma_f32_16x16x32_bf16 v[50:53], v[160:163], v[182:185], v[50:53]
	v_mfma_f32_16x16x32_bf16 v[50:53], v[170:173], v[186:189], v[50:53]
	v_mfma_f32_16x16x32_bf16 v[42:45], v[178:181], v[186:189], v[42:45]
	v_mfma_f32_16x16x32_bf16 v[42:45], v[174:177], v[182:185], v[42:45]
	v_mfma_f32_16x16x32_bf16 v[26:29], v[174:177], v[190:193], v[26:29]
	v_mfma_f32_16x16x32_bf16 v[26:29], v[178:181], v[194:197], v[26:29]
	v_mfma_f32_16x16x32_bf16 v[34:37], v[170:173], v[194:197], v[34:37]
	v_mfma_f32_16x16x32_bf16 v[34:37], v[160:163], v[190:193], v[34:37]
	v_mfma_f32_16x16x32_bf16 v[46:49], v[152:155], v[190:193], v[46:49]
	v_mfma_f32_16x16x32_bf16 v[46:49], v[156:159], v[194:197], v[46:49]
	v_mfma_f32_16x16x32_bf16 v[54:57], v[148:151], v[194:197], v[54:57]
	v_mfma_f32_16x16x32_bf16 v[54:57], v[144:147], v[190:193], v[54:57]
	s_setprio 0
	s_setprio 1
	v_mfma_f32_16x16x32_bf16 v[38:41], v[144:147], v[198:201], v[38:41]
	v_mfma_f32_16x16x32_bf16 v[38:41], v[148:151], v[202:205], v[38:41]
	v_mfma_f32_16x16x32_bf16 v[30:33], v[156:159], v[202:205], v[30:33]
	v_mfma_f32_16x16x32_bf16 v[30:33], v[152:155], v[198:201], v[30:33]
	v_mfma_f32_16x16x32_bf16 v[18:21], v[160:163], v[198:201], v[18:21]
	v_mfma_f32_16x16x32_bf16 v[18:21], v[170:173], v[202:205], v[18:21]
	v_mfma_f32_16x16x32_bf16 v[10:13], v[178:181], v[202:205], v[10:13]
	v_mfma_f32_16x16x32_bf16 v[10:13], v[174:177], v[198:201], v[10:13]
	v_mfma_f32_16x16x32_bf16 v[2:5], v[174:177], v[206:209], v[2:5]
	v_mfma_f32_16x16x32_bf16 v[2:5], v[178:181], v[210:213], v[2:5]
	v_mfma_f32_16x16x32_bf16 v[6:9], v[170:173], v[210:213], v[6:9]
	v_mfma_f32_16x16x32_bf16 v[6:9], v[160:163], v[206:209], v[6:9]
	v_mfma_f32_16x16x32_bf16 v[14:17], v[152:155], v[206:209], v[14:17]
	v_mfma_f32_16x16x32_bf16 v[14:17], v[156:159], v[210:213], v[14:17]
	v_mfma_f32_16x16x32_bf16 v[22:25], v[148:151], v[210:213], v[22:25]
	v_mfma_f32_16x16x32_bf16 v[22:25], v[144:147], v[206:209], v[22:25]
	s_setprio 0
	s_barrier
	s_add_i32 s23, 0, 0x18000
	s_add_i32 s26, 0, 0x1c000
	v_add_u32_e32 v156, s23, v165
	v_add_u32_e32 v169, s26, v165
	ds_read_b128 v[144:147], v156
	ds_read_b128 v[148:151], v156 offset:1024
	ds_read_b128 v[152:155], v156 offset:2048
	ds_read_b128 v[156:159], v156 offset:3072
	ds_read_b128 v[160:163], v169
	ds_read_b128 v[170:173], v169 offset:1024
	ds_read_b128 v[174:177], v169 offset:2048
	ds_read_b128 v[178:181], v169 offset:3072
	s_add_u32 s24, s68, 0x80000
	s_addc_u32 s25, s69, 0
	s_mov_b32 m0, s42
	v_lshl_add_u64 v[240:241], s[24:25], 0, v[130:131]
	ds_read_b128 v[182:185], v168 offset:32768
	ds_read_b128 v[186:189], v168 offset:33792
	ds_read_b128 v[190:193], v168 offset:34816
	ds_read_b128 v[194:197], v168 offset:35840
	ds_read_b128 v[198:201], v168 offset:36864
	ds_read_b128 v[202:205], v168 offset:37888
	ds_read_b128 v[206:209], v168 offset:38912
	ds_read_b128 v[210:213], v168 offset:39936
	global_load_lds_dwordx4 v[240:241], off
	v_lshl_add_u64 v[240:241], s[24:25], 0, v[134:135]
	s_mov_b32 m0, s6
	s_nop 0
	global_load_lds_dwordx4 v[240:241], off
	s_waitcnt vmcnt(8)
	s_waitcnt lgkmcnt(0)
	s_barrier
	s_setprio 1
	s_waitcnt lgkmcnt(0)
	v_mfma_f32_16x16x32_bf16 v[126:129], v[144:147], v[182:185], v[126:129]
	v_mfma_f32_16x16x32_bf16 v[126:129], v[148:151], v[186:189], v[126:129]
	v_mfma_f32_16x16x32_bf16 v[122:125], v[156:159], v[186:189], v[122:125]
	v_mfma_f32_16x16x32_bf16 v[122:125], v[152:155], v[182:185], v[122:125]
	v_mfma_f32_16x16x32_bf16 v[118:121], v[160:163], v[182:185], v[118:121]
	v_mfma_f32_16x16x32_bf16 v[118:121], v[170:173], v[186:189], v[118:121]
	v_mfma_f32_16x16x32_bf16 v[114:117], v[178:181], v[186:189], v[114:117]
	v_mfma_f32_16x16x32_bf16 v[114:117], v[174:177], v[182:185], v[114:117]
	v_mfma_f32_16x16x32_bf16 v[90:93], v[174:177], v[190:193], v[90:93]
	v_mfma_f32_16x16x32_bf16 v[90:93], v[178:181], v[194:197], v[90:93]
	v_mfma_f32_16x16x32_bf16 v[98:101], v[170:173], v[194:197], v[98:101]
	v_mfma_f32_16x16x32_bf16 v[98:101], v[160:163], v[190:193], v[98:101]
	v_mfma_f32_16x16x32_bf16 v[106:109], v[152:155], v[190:193], v[106:109]
	v_mfma_f32_16x16x32_bf16 v[106:109], v[156:159], v[194:197], v[106:109]
	v_mfma_f32_16x16x32_bf16 v[110:113], v[148:151], v[194:197], v[110:113]
	v_mfma_f32_16x16x32_bf16 v[110:113], v[144:147], v[190:193], v[110:113]
	s_setprio 0
	s_setprio 1
	v_mfma_f32_16x16x32_bf16 v[102:105], v[144:147], v[198:201], v[102:105]
	v_mfma_f32_16x16x32_bf16 v[102:105], v[148:151], v[202:205], v[102:105]
	v_mfma_f32_16x16x32_bf16 v[94:97], v[156:159], v[202:205], v[94:97]
	v_mfma_f32_16x16x32_bf16 v[94:97], v[152:155], v[198:201], v[94:97]
	v_mfma_f32_16x16x32_bf16 v[82:85], v[160:163], v[198:201], v[82:85]
	v_mfma_f32_16x16x32_bf16 v[82:85], v[170:173], v[202:205], v[82:85]
	v_mfma_f32_16x16x32_bf16 v[74:77], v[178:181], v[202:205], v[74:77]
	v_mfma_f32_16x16x32_bf16 v[74:77], v[174:177], v[198:201], v[74:77]
	v_mfma_f32_16x16x32_bf16 v[66:69], v[174:177], v[206:209], v[66:69]
	v_mfma_f32_16x16x32_bf16 v[66:69], v[178:181], v[210:213], v[66:69]
	v_mfma_f32_16x16x32_bf16 v[70:73], v[170:173], v[210:213], v[70:73]
	v_mfma_f32_16x16x32_bf16 v[70:73], v[160:163], v[206:209], v[70:73]
	v_mfma_f32_16x16x32_bf16 v[78:81], v[152:155], v[206:209], v[78:81]
	v_mfma_f32_16x16x32_bf16 v[78:81], v[156:159], v[210:213], v[78:81]
	v_mfma_f32_16x16x32_bf16 v[86:89], v[148:151], v[210:213], v[86:89]
	v_mfma_f32_16x16x32_bf16 v[86:89], v[144:147], v[206:209], v[86:89]
	s_setprio 0
	s_barrier
	s_add_i32 s23, s23, s16
	v_lshl_add_u64 v[232:233], v[232:233], 0, s[62:63]
	s_mov_b32 m0, s23
	ds_read_b128 v[182:185], v168 offset:49152
	ds_read_b128 v[186:189], v168 offset:50176
	ds_read_b128 v[190:193], v168 offset:51200
	ds_read_b128 v[194:197], v168 offset:52224
	ds_read_b128 v[198:201], v168 offset:53248
	ds_read_b128 v[202:205], v168 offset:54272
	ds_read_b128 v[206:209], v168 offset:55296
	ds_read_b128 v[210:213], v168 offset:56320
	global_load_lds_dwordx4 v[232:233], off
	s_add_i32 m0, s23, 0x2000
	s_add_u32 s24, s50, 0x80080
	v_lshl_add_u64 v[232:233], v[234:235], 0, s[62:63]
	s_addc_u32 s25, s51, 0
	s_add_i32 s23, s26, s16
	global_load_lds_dwordx4 v[232:233], off
	v_lshl_add_u64 v[232:233], s[24:25], 0, v[132:133]
	s_mov_b32 m0, s23
	s_nop 0
	global_load_lds_dwordx4 v[232:233], off
	v_lshl_add_u64 v[232:233], s[24:25], 0, v[136:137]
	s_add_i32 m0, s23, 0x2000
	s_nop 0
	global_load_lds_dwordx4 v[232:233], off
	v_lshl_add_u64 v[232:233], v[236:237], 0, s[62:63]
	s_mov_b32 m0, s76
	s_nop 0
	global_load_lds_dwordx4 v[232:233], off
	v_lshl_add_u64 v[232:233], v[238:239], 0, s[62:63]
	s_mov_b32 m0, s77
	s_nop 0
	global_load_lds_dwordx4 v[232:233], off
	s_waitcnt vmcnt(8)
	s_waitcnt lgkmcnt(0)
	s_barrier
	s_setprio 1
	s_waitcnt lgkmcnt(0)
	v_mfma_f32_16x16x32_bf16 v[62:65], v[144:147], v[182:185], v[62:65]
	v_mfma_f32_16x16x32_bf16 v[62:65], v[148:151], v[186:189], v[62:65]
	v_mfma_f32_16x16x32_bf16 v[58:61], v[156:159], v[186:189], v[58:61]
	v_mfma_f32_16x16x32_bf16 v[58:61], v[152:155], v[182:185], v[58:61]
	v_mfma_f32_16x16x32_bf16 v[50:53], v[160:163], v[182:185], v[50:53]
	v_mfma_f32_16x16x32_bf16 v[50:53], v[170:173], v[186:189], v[50:53]
	v_mfma_f32_16x16x32_bf16 v[42:45], v[178:181], v[186:189], v[42:45]
	v_mfma_f32_16x16x32_bf16 v[42:45], v[174:177], v[182:185], v[42:45]
	v_mfma_f32_16x16x32_bf16 v[26:29], v[174:177], v[190:193], v[26:29]
	v_mfma_f32_16x16x32_bf16 v[26:29], v[178:181], v[194:197], v[26:29]
	v_mfma_f32_16x16x32_bf16 v[34:37], v[170:173], v[194:197], v[34:37]
	v_mfma_f32_16x16x32_bf16 v[34:37], v[160:163], v[190:193], v[34:37]
	v_mfma_f32_16x16x32_bf16 v[46:49], v[152:155], v[190:193], v[46:49]
	v_mfma_f32_16x16x32_bf16 v[46:49], v[156:159], v[194:197], v[46:49]
	v_mfma_f32_16x16x32_bf16 v[54:57], v[148:151], v[194:197], v[54:57]
	v_mfma_f32_16x16x32_bf16 v[54:57], v[144:147], v[190:193], v[54:57]
	s_setprio 0
	s_setprio 1
	v_mfma_f32_16x16x32_bf16 v[38:41], v[144:147], v[198:201], v[38:41]
	v_mfma_f32_16x16x32_bf16 v[38:41], v[148:151], v[202:205], v[38:41]
	v_mfma_f32_16x16x32_bf16 v[30:33], v[156:159], v[202:205], v[30:33]
	v_mfma_f32_16x16x32_bf16 v[30:33], v[152:155], v[198:201], v[30:33]
	v_mfma_f32_16x16x32_bf16 v[18:21], v[160:163], v[198:201], v[18:21]
	v_mfma_f32_16x16x32_bf16 v[18:21], v[170:173], v[202:205], v[18:21]
	v_mfma_f32_16x16x32_bf16 v[10:13], v[178:181], v[202:205], v[10:13]
	v_mfma_f32_16x16x32_bf16 v[10:13], v[174:177], v[198:201], v[10:13]
	v_mfma_f32_16x16x32_bf16 v[2:5], v[174:177], v[206:209], v[2:5]
	v_mfma_f32_16x16x32_bf16 v[2:5], v[178:181], v[210:213], v[2:5]
	v_mfma_f32_16x16x32_bf16 v[6:9], v[170:173], v[210:213], v[6:9]
	v_mfma_f32_16x16x32_bf16 v[6:9], v[160:163], v[206:209], v[6:9]
	v_mfma_f32_16x16x32_bf16 v[14:17], v[152:155], v[206:209], v[14:17]
	v_mfma_f32_16x16x32_bf16 v[14:17], v[156:159], v[210:213], v[14:17]
	v_mfma_f32_16x16x32_bf16 v[22:25], v[148:151], v[210:213], v[22:25]
	v_mfma_f32_16x16x32_bf16 v[22:25], v[144:147], v[206:209], v[22:25]
	s_setprio 0
	s_barrier
	s_add_i32 s22, s22, 2
	s_add_u32 s48, s48, 0x100
	s_addc_u32 s49, s49, 0
	s_add_u32 s20, s20, 0x100
	s_addc_u32 s21, s21, 0
	s_cmp_gt_u32 s22, 29
	s_cbranch_scc0 .LBB0_132
	s_and_b64 vcc, exec, s[10:11]
	s_cbranch_vccz .LBB0_135
	s_barrier

.LBB0_238:
	s_add_u32 s10, s12, 0x100
	s_addc_u32 s11, s13, 0
	s_add_i32 s23, 0, 0x10000
	s_cmpk_eq_i32 s22, 0x52
	s_cselect_b32 vcc_hi, s47, s11
	s_cselect_b32 vcc_lo, s46, s10
	s_cselect_b32 s51, s49, s21
	s_cselect_b32 s50, s48, s20
	s_add_i32 s24, 0, 0x14000
	v_add_u32_e32 v142, s23, v194
	v_add_u32_e32 v158, s24, v194
	ds_read_b128 v[122:125], v142
	ds_read_b128 v[126:129], v142 offset:1024
	ds_read_b128 v[138:141], v142 offset:2048
	ds_read_b128 v[142:145], v142 offset:3072
	ds_read_b128 v[146:149], v158
	ds_read_b128 v[150:153], v158 offset:1024
	ds_read_b128 v[154:157], v158 offset:2048
	ds_read_b128 v[158:161], v158 offset:3072
	v_lshl_add_u64 v[212:213], s[12:13], 0, v[170:171]
	s_add_i32 m0, s57, 0xc000
	ds_read_b128 v[174:177], v198
	ds_read_b128 v[178:181], v198 offset:1024
	ds_read_b128 v[182:185], v198 offset:2048
	ds_read_b128 v[186:189], v198 offset:3072
	ds_read_b128 v[190:193], v198 offset:4096
	ds_read_b128 v[200:203], v198 offset:5120
	ds_read_b128 v[204:207], v198 offset:6144
	ds_read_b128 v[208:211], v198 offset:7168
	global_load_lds_dwordx4 v[212:213], off
	v_lshl_add_u64 v[212:213], s[12:13], 0, v[172:173]
	s_add_i32 m0, s57, 0xe000
	s_nop 0
	global_load_lds_dwordx4 v[212:213], off
	s_waitcnt vmcnt(8)
	s_waitcnt lgkmcnt(0)
	s_barrier
	s_setprio 1
	s_waitcnt lgkmcnt(0)
	v_mfma_f32_16x16x32_bf16 v[134:137], v[122:125], v[174:177], v[134:137]
	v_mfma_f32_16x16x32_bf16 v[134:137], v[126:129], v[178:181], v[134:137]
	v_mfma_f32_16x16x32_bf16 v[130:133], v[142:145], v[178:181], v[130:133]
	v_mfma_f32_16x16x32_bf16 v[130:133], v[138:141], v[174:177], v[130:133]
	v_mfma_f32_16x16x32_bf16 v[118:121], v[146:149], v[174:177], v[118:121]
	v_mfma_f32_16x16x32_bf16 v[118:121], v[150:153], v[178:181], v[118:121]
	v_mfma_f32_16x16x32_bf16 v[114:117], v[158:161], v[178:181], v[114:117]
	v_mfma_f32_16x16x32_bf16 v[114:117], v[154:157], v[174:177], v[114:117]
	v_mfma_f32_16x16x32_bf16 v[98:101], v[154:157], v[182:185], v[98:101]
	v_mfma_f32_16x16x32_bf16 v[98:101], v[158:161], v[186:189], v[98:101]
	v_mfma_f32_16x16x32_bf16 v[102:105], v[150:153], v[186:189], v[102:105]
	v_mfma_f32_16x16x32_bf16 v[102:105], v[146:149], v[182:185], v[102:105]
	v_mfma_f32_16x16x32_bf16 v[106:109], v[138:141], v[182:185], v[106:109]
	v_mfma_f32_16x16x32_bf16 v[106:109], v[142:145], v[186:189], v[106:109]
	v_mfma_f32_16x16x32_bf16 v[110:113], v[126:129], v[186:189], v[110:113]
	v_mfma_f32_16x16x32_bf16 v[110:113], v[122:125], v[182:185], v[110:113]
	s_setprio 0
	s_setprio 1
	v_mfma_f32_16x16x32_bf16 v[94:97], v[122:125], v[190:193], v[94:97]
	v_mfma_f32_16x16x32_bf16 v[94:97], v[126:129], v[200:203], v[94:97]
	v_mfma_f32_16x16x32_bf16 v[90:93], v[142:145], v[200:203], v[90:93]
	v_mfma_f32_16x16x32_bf16 v[90:93], v[138:141], v[190:193], v[90:93]
	v_mfma_f32_16x16x32_bf16 v[86:89], v[146:149], v[190:193], v[86:89]
	v_mfma_f32_16x16x32_bf16 v[86:89], v[150:153], v[200:203], v[86:89]
	v_mfma_f32_16x16x32_bf16 v[82:85], v[158:161], v[200:203], v[82:85]
	v_mfma_f32_16x16x32_bf16 v[82:85], v[154:157], v[190:193], v[82:85]
	v_mfma_f32_16x16x32_bf16 v[66:69], v[154:157], v[204:207], v[66:69]
	v_mfma_f32_16x16x32_bf16 v[66:69], v[158:161], v[208:211], v[66:69]
	v_mfma_f32_16x16x32_bf16 v[70:73], v[150:153], v[208:211], v[70:73]
	v_mfma_f32_16x16x32_bf16 v[70:73], v[146:149], v[204:207], v[70:73]
	v_mfma_f32_16x16x32_bf16 v[74:77], v[138:141], v[204:207], v[74:77]
	v_mfma_f32_16x16x32_bf16 v[74:77], v[142:145], v[208:211], v[74:77]
	v_mfma_f32_16x16x32_bf16 v[78:81], v[126:129], v[208:211], v[78:81]
	v_mfma_f32_16x16x32_bf16 v[78:81], v[122:125], v[204:207], v[78:81]
	s_setprio 0
	s_barrier
	s_add_i32 s12, s23, s42
	v_lshl_add_u64 v[212:213], s[50:51], 0, v[164:165]
	s_mov_b32 m0, s12
	ds_read_b128 v[174:177], v198 offset:16384
	ds_read_b128 v[178:181], v198 offset:17408
	ds_read_b128 v[182:185], v198 offset:18432
	ds_read_b128 v[186:189], v198 offset:19456
	ds_read_b128 v[190:193], v198 offset:20480
	ds_read_b128 v[200:203], v198 offset:21504
	ds_read_b128 v[204:207], v198 offset:22528
	ds_read_b128 v[208:211], v198 offset:23552
	global_load_lds_dwordx4 v[212:213], off
	s_add_i32 m0, s12, 0x2000
	s_add_u32 s12, s50, 0x158000
	v_lshl_add_u64 v[232:233], s[50:51], 0, v[168:169]
	s_addc_u32 s13, s51, 0
	s_add_i32 s23, s24, s42
	global_load_lds_dwordx4 v[232:233], off
	v_lshl_add_u64 v[234:235], s[12:13], 0, v[164:165]
	s_mov_b32 m0, s23
	v_lshl_add_u64 v[236:237], vcc, 0, v[166:167]
	global_load_lds_dwordx4 v[234:235], off
	v_lshl_add_u64 v[234:235], s[12:13], 0, v[168:169]
	s_add_i32 m0, s23, 0x2000
	s_nop 0
	global_load_lds_dwordx4 v[234:235], off
	v_lshl_add_u64 v[234:235], vcc, 0, v[162:163]
	s_mov_b32 m0, s57
	s_nop 0
	global_load_lds_dwordx4 v[234:235], off
	s_mov_b32 m0, s58
	s_nop 0
	global_load_lds_dwordx4 v[236:237], off
	s_waitcnt vmcnt(8)
	s_waitcnt lgkmcnt(0)
	s_barrier
	s_setprio 1
	s_waitcnt lgkmcnt(0)
	v_mfma_f32_16x16x32_bf16 v[62:65], v[122:125], v[174:177], v[62:65]
	v_mfma_f32_16x16x32_bf16 v[62:65], v[126:129], v[178:181], v[62:65]
	v_mfma_f32_16x16x32_bf16 v[58:61], v[142:145], v[178:181], v[58:61]
	v_mfma_f32_16x16x32_bf16 v[58:61], v[138:141], v[174:177], v[58:61]
	v_mfma_f32_16x16x32_bf16 v[54:57], v[146:149], v[174:177], v[54:57]
	v_mfma_f32_16x16x32_bf16 v[54:57], v[150:153], v[178:181], v[54:57]
	v_mfma_f32_16x16x32_bf16 v[50:53], v[158:161], v[178:181], v[50:53]
	v_mfma_f32_16x16x32_bf16 v[50:53], v[154:157], v[174:177], v[50:53]
	v_mfma_f32_16x16x32_bf16 v[34:37], v[154:157], v[182:185], v[34:37]
	v_mfma_f32_16x16x32_bf16 v[34:37], v[158:161], v[186:189], v[34:37]
	v_mfma_f32_16x16x32_bf16 v[38:41], v[150:153], v[186:189], v[38:41]
	v_mfma_f32_16x16x32_bf16 v[38:41], v[146:149], v[182:185], v[38:41]
	v_mfma_f32_16x16x32_bf16 v[42:45], v[138:141], v[182:185], v[42:45]
	v_mfma_f32_16x16x32_bf16 v[42:45], v[142:145], v[186:189], v[42:45]
	v_mfma_f32_16x16x32_bf16 v[46:49], v[126:129], v[186:189], v[46:49]
	v_mfma_f32_16x16x32_bf16 v[46:49], v[122:125], v[182:185], v[46:49]
	s_setprio 0
	s_setprio 1
	v_mfma_f32_16x16x32_bf16 v[30:33], v[122:125], v[190:193], v[30:33]
	v_mfma_f32_16x16x32_bf16 v[30:33], v[126:129], v[200:203], v[30:33]
	v_mfma_f32_16x16x32_bf16 v[26:29], v[142:145], v[200:203], v[26:29]
	v_mfma_f32_16x16x32_bf16 v[26:29], v[138:141], v[190:193], v[26:29]
	v_mfma_f32_16x16x32_bf16 v[22:25], v[146:149], v[190:193], v[22:25]
	v_mfma_f32_16x16x32_bf16 v[22:25], v[150:153], v[200:203], v[22:25]
	v_mfma_f32_16x16x32_bf16 v[18:21], v[158:161], v[200:203], v[18:21]
	v_mfma_f32_16x16x32_bf16 v[18:21], v[154:157], v[190:193], v[18:21]
	v_mfma_f32_16x16x32_bf16 v[2:5], v[154:157], v[204:207], v[2:5]
	v_mfma_f32_16x16x32_bf16 v[2:5], v[158:161], v[208:211], v[2:5]
	v_mfma_f32_16x16x32_bf16 v[6:9], v[150:153], v[208:211], v[6:9]
	v_mfma_f32_16x16x32_bf16 v[6:9], v[146:149], v[204:207], v[6:9]
	v_mfma_f32_16x16x32_bf16 v[10:13], v[138:141], v[204:207], v[10:13]
	v_mfma_f32_16x16x32_bf16 v[10:13], v[142:145], v[208:211], v[10:13]
	v_mfma_f32_16x16x32_bf16 v[14:17], v[126:129], v[208:211], v[14:17]
	v_mfma_f32_16x16x32_bf16 v[14:17], v[122:125], v[204:207], v[14:17]
	s_setprio 0
	s_barrier
	s_add_i32 s23, 0, 0x18000
	s_add_i32 s24, 0, 0x1c000
	v_add_u32_e32 v142, s23, v194
	v_add_u32_e32 v158, s24, v194
	ds_read_b128 v[122:125], v142
	ds_read_b128 v[126:129], v142 offset:1024
	ds_read_b128 v[138:141], v142 offset:2048
	ds_read_b128 v[142:145], v142 offset:3072
	ds_read_b128 v[146:149], v158
	ds_read_b128 v[150:153], v158 offset:1024
	ds_read_b128 v[154:157], v158 offset:2048
	ds_read_b128 v[158:161], v158 offset:3072
	s_add_u32 s12, vcc_lo, 0x158000
	s_addc_u32 s13, vcc_hi, 0
	s_mov_b32 m0, s67
	v_lshl_add_u64 v[238:239], s[12:13], 0, v[162:163]
	ds_read_b128 v[174:177], v198 offset:32768
	ds_read_b128 v[178:181], v198 offset:33792
	ds_read_b128 v[182:185], v198 offset:34816
	ds_read_b128 v[186:189], v198 offset:35840
	ds_read_b128 v[190:193], v198 offset:36864
	ds_read_b128 v[200:203], v198 offset:37888
	ds_read_b128 v[204:207], v198 offset:38912
	ds_read_b128 v[208:211], v198 offset:39936
	global_load_lds_dwordx4 v[238:239], off
	v_lshl_add_u64 v[238:239], s[12:13], 0, v[166:167]
	s_mov_b32 m0, s76
	s_nop 0
	global_load_lds_dwordx4 v[238:239], off
	s_waitcnt vmcnt(8)
	s_waitcnt lgkmcnt(0)
	s_barrier
	s_setprio 1
	s_waitcnt lgkmcnt(0)
	v_mfma_f32_16x16x32_bf16 v[134:137], v[122:125], v[174:177], v[134:137]
	v_mfma_f32_16x16x32_bf16 v[134:137], v[126:129], v[178:181], v[134:137]
	v_mfma_f32_16x16x32_bf16 v[130:133], v[142:145], v[178:181], v[130:133]
	v_mfma_f32_16x16x32_bf16 v[130:133], v[138:141], v[174:177], v[130:133]
	v_mfma_f32_16x16x32_bf16 v[118:121], v[146:149], v[174:177], v[118:121]
	v_mfma_f32_16x16x32_bf16 v[118:121], v[150:153], v[178:181], v[118:121]
	v_mfma_f32_16x16x32_bf16 v[114:117], v[158:161], v[178:181], v[114:117]
	v_mfma_f32_16x16x32_bf16 v[114:117], v[154:157], v[174:177], v[114:117]
	v_mfma_f32_16x16x32_bf16 v[98:101], v[154:157], v[182:185], v[98:101]
	v_mfma_f32_16x16x32_bf16 v[98:101], v[158:161], v[186:189], v[98:101]
	v_mfma_f32_16x16x32_bf16 v[102:105], v[150:153], v[186:189], v[102:105]
	v_mfma_f32_16x16x32_bf16 v[102:105], v[146:149], v[182:185], v[102:105]
	v_mfma_f32_16x16x32_bf16 v[106:109], v[138:141], v[182:185], v[106:109]
	v_mfma_f32_16x16x32_bf16 v[106:109], v[142:145], v[186:189], v[106:109]
	v_mfma_f32_16x16x32_bf16 v[110:113], v[126:129], v[186:189], v[110:113]
	v_mfma_f32_16x16x32_bf16 v[110:113], v[122:125], v[182:185], v[110:113]
	s_setprio 0
	s_setprio 1
	v_mfma_f32_16x16x32_bf16 v[94:97], v[122:125], v[190:193], v[94:97]
	v_mfma_f32_16x16x32_bf16 v[94:97], v[126:129], v[200:203], v[94:97]
	v_mfma_f32_16x16x32_bf16 v[90:93], v[142:145], v[200:203], v[90:93]
	v_mfma_f32_16x16x32_bf16 v[90:93], v[138:141], v[190:193], v[90:93]
	v_mfma_f32_16x16x32_bf16 v[86:89], v[146:149], v[190:193], v[86:89]
	v_mfma_f32_16x16x32_bf16 v[86:89], v[150:153], v[200:203], v[86:89]
	v_mfma_f32_16x16x32_bf16 v[82:85], v[158:161], v[200:203], v[82:85]
	v_mfma_f32_16x16x32_bf16 v[82:85], v[154:157], v[190:193], v[82:85]
	v_mfma_f32_16x16x32_bf16 v[66:69], v[154:157], v[204:207], v[66:69]
	v_mfma_f32_16x16x32_bf16 v[66:69], v[158:161], v[208:211], v[66:69]
	v_mfma_f32_16x16x32_bf16 v[70:73], v[150:153], v[208:211], v[70:73]
	v_mfma_f32_16x16x32_bf16 v[70:73], v[146:149], v[204:207], v[70:73]
	v_mfma_f32_16x16x32_bf16 v[74:77], v[138:141], v[204:207], v[74:77]
	v_mfma_f32_16x16x32_bf16 v[74:77], v[142:145], v[208:211], v[74:77]
	v_mfma_f32_16x16x32_bf16 v[78:81], v[126:129], v[208:211], v[78:81]
	v_mfma_f32_16x16x32_bf16 v[78:81], v[122:125], v[204:207], v[78:81]
	s_setprio 0
	s_barrier
	s_add_i32 s12, s23, s42
	v_lshl_add_u64 v[212:213], v[212:213], 0, s[62:63]
	s_mov_b32 m0, s12
	ds_read_b128 v[174:177], v198 offset:49152
	ds_read_b128 v[178:181], v198 offset:50176
	ds_read_b128 v[182:185], v198 offset:51200
	ds_read_b128 v[186:189], v198 offset:52224
	ds_read_b128 v[190:193], v198 offset:53248
	ds_read_b128 v[200:203], v198 offset:54272
	ds_read_b128 v[204:207], v198 offset:55296
	ds_read_b128 v[208:211], v198 offset:56320
	global_load_lds_dwordx4 v[212:213], off
	s_add_i32 m0, s12, 0x2000
	s_add_u32 s12, s50, 0x158080
	v_lshl_add_u64 v[212:213], v[232:233], 0, s[62:63]
	s_addc_u32 s13, s51, 0
	s_add_i32 s23, s24, s42
	global_load_lds_dwordx4 v[212:213], off
	v_lshl_add_u64 v[212:213], s[12:13], 0, v[164:165]
	s_mov_b32 m0, s23
	s_nop 0
	global_load_lds_dwordx4 v[212:213], off
	v_lshl_add_u64 v[212:213], s[12:13], 0, v[168:169]
	s_add_i32 m0, s23, 0x2000
	s_nop 0
	global_load_lds_dwordx4 v[212:213], off
	v_lshl_add_u64 v[212:213], v[234:235], 0, s[62:63]
	s_mov_b32 m0, s1
	s_nop 0
	global_load_lds_dwordx4 v[212:213], off
	v_lshl_add_u64 v[212:213], v[236:237], 0, s[62:63]
	s_mov_b32 m0, s52
	s_nop 0
	global_load_lds_dwordx4 v[212:213], off
	s_waitcnt vmcnt(8)
	s_waitcnt lgkmcnt(0)
	s_barrier
	s_setprio 1
	s_waitcnt lgkmcnt(0)
	v_mfma_f32_16x16x32_bf16 v[62:65], v[122:125], v[174:177], v[62:65]
	v_mfma_f32_16x16x32_bf16 v[62:65], v[126:129], v[178:181], v[62:65]
	v_mfma_f32_16x16x32_bf16 v[58:61], v[142:145], v[178:181], v[58:61]
	v_mfma_f32_16x16x32_bf16 v[58:61], v[138:141], v[174:177], v[58:61]
	v_mfma_f32_16x16x32_bf16 v[54:57], v[146:149], v[174:177], v[54:57]
	v_mfma_f32_16x16x32_bf16 v[54:57], v[150:153], v[178:181], v[54:57]
	v_mfma_f32_16x16x32_bf16 v[50:53], v[158:161], v[178:181], v[50:53]
	v_mfma_f32_16x16x32_bf16 v[50:53], v[154:157], v[174:177], v[50:53]
	v_mfma_f32_16x16x32_bf16 v[34:37], v[154:157], v[182:185], v[34:37]
	v_mfma_f32_16x16x32_bf16 v[34:37], v[158:161], v[186:189], v[34:37]
	v_mfma_f32_16x16x32_bf16 v[38:41], v[150:153], v[186:189], v[38:41]
	v_mfma_f32_16x16x32_bf16 v[38:41], v[146:149], v[182:185], v[38:41]
	v_mfma_f32_16x16x32_bf16 v[42:45], v[138:141], v[182:185], v[42:45]
	v_mfma_f32_16x16x32_bf16 v[42:45], v[142:145], v[186:189], v[42:45]
	v_mfma_f32_16x16x32_bf16 v[46:49], v[126:129], v[186:189], v[46:49]
	v_mfma_f32_16x16x32_bf16 v[46:49], v[122:125], v[182:185], v[46:49]
	s_setprio 0
	s_setprio 1
	v_mfma_f32_16x16x32_bf16 v[30:33], v[122:125], v[190:193], v[30:33]
	v_mfma_f32_16x16x32_bf16 v[30:33], v[126:129], v[200:203], v[30:33]
	v_mfma_f32_16x16x32_bf16 v[26:29], v[142:145], v[200:203], v[26:29]
	v_mfma_f32_16x16x32_bf16 v[26:29], v[138:141], v[190:193], v[26:29]
	v_mfma_f32_16x16x32_bf16 v[22:25], v[146:149], v[190:193], v[22:25]
	v_mfma_f32_16x16x32_bf16 v[22:25], v[150:153], v[200:203], v[22:25]
	v_mfma_f32_16x16x32_bf16 v[18:21], v[158:161], v[200:203], v[18:21]
	v_mfma_f32_16x16x32_bf16 v[18:21], v[154:157], v[190:193], v[18:21]
	v_mfma_f32_16x16x32_bf16 v[2:5], v[154:157], v[204:207], v[2:5]
	v_mfma_f32_16x16x32_bf16 v[2:5], v[158:161], v[208:211], v[2:5]
	v_mfma_f32_16x16x32_bf16 v[6:9], v[150:153], v[208:211], v[6:9]
	v_mfma_f32_16x16x32_bf16 v[6:9], v[146:149], v[204:207], v[6:9]
	v_mfma_f32_16x16x32_bf16 v[10:13], v[138:141], v[204:207], v[10:13]
	v_mfma_f32_16x16x32_bf16 v[10:13], v[142:145], v[208:211], v[10:13]
	v_mfma_f32_16x16x32_bf16 v[14:17], v[126:129], v[208:211], v[14:17]
	v_mfma_f32_16x16x32_bf16 v[14:17], v[122:125], v[204:207], v[14:17]
	s_setprio 0
	s_barrier
	s_add_i32 s22, s22, 2
	s_add_u32 s20, s20, 0x100
	s_addc_u32 s21, s21, 0
	s_cmpk_gt_u32 s22, 0x53
	s_mov_b64 s[12:13], s[10:11]
	s_cbranch_scc0 .LBB0_238
	s_and_b64 vcc, exec, s[2:3]
	s_cbranch_vccz .LBB0_241
	s_barrier

.LBB0_340:
	s_add_u32 s22, s46, 0xfff80080
	s_addc_u32 s23, s47, -1
	s_add_i32 s24, 0, 0x10000
	s_cmp_eq_u32 s21, 28
	s_cselect_b32 s51, s1, s23
	s_cselect_b32 s50, s13, s22
	v_add_u32_e32 v148, s24, v152
	s_cselect_b32 s49, s11, s20
	s_cselect_b32 s48, s18, s19
	s_add_i32 s25, 0, 0x14000
	ds_read_b128 v[144:147], v148
	ds_read_b128 v[156:159], v148 offset:1024
	ds_read_b128 v[160:163], v148 offset:2048
	ds_read_b128 v[164:167], v148 offset:3072
	v_add_u32_e32 v148, s25, v152
	ds_read_b128 v[168:171], v148
	ds_read_b128 v[172:175], v148 offset:1024
	ds_read_b128 v[176:179], v148 offset:2048
	ds_read_b128 v[180:183], v148 offset:3072
	v_lshl_add_u64 v[148:149], s[46:47], 0, v[140:141]
	s_add_i32 m0, s3, 0xc000
	ds_read_b128 v[184:187], v154
	ds_read_b128 v[188:191], v154 offset:1024
	ds_read_b128 v[192:195], v154 offset:2048
	ds_read_b128 v[196:199], v154 offset:3072
	ds_read_b128 v[200:203], v154 offset:4096
	ds_read_b128 v[204:207], v154 offset:5120
	ds_read_b128 v[208:211], v154 offset:6144
	ds_read_b128 v[232:235], v154 offset:7168
	global_load_lds_dwordx4 v[148:149], off
	v_lshl_add_u64 v[148:149], s[46:47], 0, v[142:143]
	s_add_i32 m0, s3, 0xe000
	s_nop 0
	global_load_lds_dwordx4 v[148:149], off
	s_waitcnt vmcnt(8)
	s_waitcnt lgkmcnt(0)
	s_barrier
	s_setprio 1
	s_waitcnt lgkmcnt(0)
	v_mfma_f32_16x16x32_bf16 v[126:129], v[144:147], v[184:187], v[126:129]
	v_mfma_f32_16x16x32_bf16 v[126:129], v[156:159], v[188:191], v[126:129]
	v_mfma_f32_16x16x32_bf16 v[122:125], v[164:167], v[188:191], v[122:125]
	v_mfma_f32_16x16x32_bf16 v[122:125], v[160:163], v[184:187], v[122:125]
	v_mfma_f32_16x16x32_bf16 v[118:121], v[168:171], v[184:187], v[118:121]
	v_mfma_f32_16x16x32_bf16 v[118:121], v[172:175], v[188:191], v[118:121]
	v_mfma_f32_16x16x32_bf16 v[114:117], v[180:183], v[188:191], v[114:117]
	v_mfma_f32_16x16x32_bf16 v[114:117], v[176:179], v[184:187], v[114:117]
	v_mfma_f32_16x16x32_bf16 v[98:101], v[176:179], v[192:195], v[98:101]
	v_mfma_f32_16x16x32_bf16 v[98:101], v[180:183], v[196:199], v[98:101]
	v_mfma_f32_16x16x32_bf16 v[102:105], v[172:175], v[196:199], v[102:105]
	v_mfma_f32_16x16x32_bf16 v[102:105], v[168:171], v[192:195], v[102:105]
	v_mfma_f32_16x16x32_bf16 v[106:109], v[160:163], v[192:195], v[106:109]
	v_mfma_f32_16x16x32_bf16 v[106:109], v[164:167], v[196:199], v[106:109]
	v_mfma_f32_16x16x32_bf16 v[110:113], v[156:159], v[196:199], v[110:113]
	v_mfma_f32_16x16x32_bf16 v[110:113], v[144:147], v[192:195], v[110:113]
	s_setprio 0
	s_setprio 1
	v_mfma_f32_16x16x32_bf16 v[94:97], v[144:147], v[200:203], v[94:97]
	v_mfma_f32_16x16x32_bf16 v[94:97], v[156:159], v[204:207], v[94:97]
	v_mfma_f32_16x16x32_bf16 v[90:93], v[164:167], v[204:207], v[90:93]
	v_mfma_f32_16x16x32_bf16 v[90:93], v[160:163], v[200:203], v[90:93]
	v_mfma_f32_16x16x32_bf16 v[86:89], v[168:171], v[200:203], v[86:89]
	v_mfma_f32_16x16x32_bf16 v[86:89], v[172:175], v[204:207], v[86:89]
	v_mfma_f32_16x16x32_bf16 v[82:85], v[180:183], v[204:207], v[82:85]
	v_mfma_f32_16x16x32_bf16 v[82:85], v[176:179], v[200:203], v[82:85]
	v_mfma_f32_16x16x32_bf16 v[66:69], v[176:179], v[208:211], v[66:69]
	v_mfma_f32_16x16x32_bf16 v[66:69], v[180:183], v[232:235], v[66:69]
	v_mfma_f32_16x16x32_bf16 v[70:73], v[172:175], v[232:235], v[70:73]
	v_mfma_f32_16x16x32_bf16 v[70:73], v[168:171], v[208:211], v[70:73]
	v_mfma_f32_16x16x32_bf16 v[74:77], v[160:163], v[208:211], v[74:77]
	v_mfma_f32_16x16x32_bf16 v[74:77], v[164:167], v[232:235], v[74:77]
	v_mfma_f32_16x16x32_bf16 v[78:81], v[156:159], v[232:235], v[78:81]
	v_mfma_f32_16x16x32_bf16 v[78:81], v[144:147], v[208:211], v[78:81]
	s_setprio 0
	s_barrier
	s_add_i32 s22, s24, s16
	v_lshl_add_u64 v[148:149], s[48:49], 0, v[134:135]
	s_mov_b32 m0, s22
	ds_read_b128 v[184:187], v154 offset:16384
	ds_read_b128 v[188:191], v154 offset:17408
	ds_read_b128 v[192:195], v154 offset:18432
	ds_read_b128 v[196:199], v154 offset:19456
	ds_read_b128 v[200:203], v154 offset:20480
	ds_read_b128 v[204:207], v154 offset:21504
	ds_read_b128 v[208:211], v154 offset:22528
	ds_read_b128 v[232:235], v154 offset:23552
	global_load_lds_dwordx4 v[148:149], off
	s_add_i32 m0, s22, 0x2000
	s_add_u32 s22, s48, 0x80000
	v_lshl_add_u64 v[212:213], s[48:49], 0, v[130:131]
	s_addc_u32 s23, s49, 0
	s_add_i32 s24, s25, s16
	global_load_lds_dwordx4 v[212:213], off
	v_lshl_add_u64 v[236:237], s[22:23], 0, v[134:135]
	s_mov_b32 m0, s24
	v_lshl_add_u64 v[238:239], s[50:51], 0, v[132:133]
	global_load_lds_dwordx4 v[236:237], off
	v_lshl_add_u64 v[236:237], s[22:23], 0, v[130:131]
	s_add_i32 m0, s24, 0x2000
	s_nop 0
	global_load_lds_dwordx4 v[236:237], off
	v_lshl_add_u64 v[236:237], s[50:51], 0, v[136:137]
	s_mov_b32 m0, s3
	s_nop 0
	global_load_lds_dwordx4 v[236:237], off
	s_mov_b32 m0, s55
	s_nop 0
	global_load_lds_dwordx4 v[238:239], off
	s_waitcnt vmcnt(8)
	s_waitcnt lgkmcnt(0)
	s_barrier
	s_setprio 1
	s_waitcnt lgkmcnt(0)
	v_mfma_f32_16x16x32_bf16 v[62:65], v[144:147], v[184:187], v[62:65]
	v_mfma_f32_16x16x32_bf16 v[62:65], v[156:159], v[188:191], v[62:65]
	v_mfma_f32_16x16x32_bf16 v[58:61], v[164:167], v[188:191], v[58:61]
	v_mfma_f32_16x16x32_bf16 v[58:61], v[160:163], v[184:187], v[58:61]
	v_mfma_f32_16x16x32_bf16 v[54:57], v[168:171], v[184:187], v[54:57]
	v_mfma_f32_16x16x32_bf16 v[54:57], v[172:175], v[188:191], v[54:57]
	v_mfma_f32_16x16x32_bf16 v[50:53], v[180:183], v[188:191], v[50:53]
	v_mfma_f32_16x16x32_bf16 v[50:53], v[176:179], v[184:187], v[50:53]
	v_mfma_f32_16x16x32_bf16 v[34:37], v[176:179], v[192:195], v[34:37]
	v_mfma_f32_16x16x32_bf16 v[34:37], v[180:183], v[196:199], v[34:37]
	v_mfma_f32_16x16x32_bf16 v[38:41], v[172:175], v[196:199], v[38:41]
	v_mfma_f32_16x16x32_bf16 v[38:41], v[168:171], v[192:195], v[38:41]
	v_mfma_f32_16x16x32_bf16 v[42:45], v[160:163], v[192:195], v[42:45]
	v_mfma_f32_16x16x32_bf16 v[42:45], v[164:167], v[196:199], v[42:45]
	v_mfma_f32_16x16x32_bf16 v[46:49], v[156:159], v[196:199], v[46:49]
	v_mfma_f32_16x16x32_bf16 v[46:49], v[144:147], v[192:195], v[46:49]
	s_setprio 0
	s_setprio 1
	v_mfma_f32_16x16x32_bf16 v[30:33], v[144:147], v[200:203], v[30:33]
	v_mfma_f32_16x16x32_bf16 v[30:33], v[156:159], v[204:207], v[30:33]
	v_mfma_f32_16x16x32_bf16 v[26:29], v[164:167], v[204:207], v[26:29]
	v_mfma_f32_16x16x32_bf16 v[26:29], v[160:163], v[200:203], v[26:29]
	v_mfma_f32_16x16x32_bf16 v[22:25], v[168:171], v[200:203], v[22:25]
	v_mfma_f32_16x16x32_bf16 v[22:25], v[172:175], v[204:207], v[22:25]
	v_mfma_f32_16x16x32_bf16 v[18:21], v[180:183], v[204:207], v[18:21]
	v_mfma_f32_16x16x32_bf16 v[18:21], v[176:179], v[200:203], v[18:21]
	v_mfma_f32_16x16x32_bf16 v[2:5], v[176:179], v[208:211], v[2:5]
	v_mfma_f32_16x16x32_bf16 v[2:5], v[180:183], v[232:235], v[2:5]
	v_mfma_f32_16x16x32_bf16 v[6:9], v[172:175], v[232:235], v[6:9]
	v_mfma_f32_16x16x32_bf16 v[6:9], v[168:171], v[208:211], v[6:9]
	v_mfma_f32_16x16x32_bf16 v[10:13], v[160:163], v[208:211], v[10:13]
	v_mfma_f32_16x16x32_bf16 v[10:13], v[164:167], v[232:235], v[10:13]
	v_mfma_f32_16x16x32_bf16 v[14:17], v[156:159], v[232:235], v[14:17]
	v_mfma_f32_16x16x32_bf16 v[14:17], v[144:147], v[208:211], v[14:17]
	s_setprio 0
	s_barrier
	s_add_i32 s24, 0, 0x18000
	v_add_u32_e32 v155, s24, v152
	s_add_i32 s25, 0, 0x1c000
	ds_read_b128 v[144:147], v155
	ds_read_b128 v[156:159], v155 offset:1024
	ds_read_b128 v[160:163], v155 offset:2048
	ds_read_b128 v[164:167], v155 offset:3072
	v_add_u32_e32 v155, s25, v152
	ds_read_b128 v[168:171], v155
	ds_read_b128 v[172:175], v155 offset:1024
	ds_read_b128 v[176:179], v155 offset:2048
	ds_read_b128 v[180:183], v155 offset:3072
	s_add_u32 s22, s50, 0x80000
	s_addc_u32 s23, s51, 0
	s_mov_b32 m0, s57
	v_lshl_add_u64 v[240:241], s[22:23], 0, v[136:137]
	ds_read_b128 v[184:187], v154 offset:32768
	ds_read_b128 v[188:191], v154 offset:33792
	ds_read_b128 v[192:195], v154 offset:34816
	ds_read_b128 v[196:199], v154 offset:35840
	ds_read_b128 v[200:203], v154 offset:36864
	ds_read_b128 v[204:207], v154 offset:37888
	ds_read_b128 v[208:211], v154 offset:38912
	ds_read_b128 v[232:235], v154 offset:39936
	global_load_lds_dwordx4 v[240:241], off
	v_lshl_add_u64 v[240:241], s[22:23], 0, v[132:133]
	s_mov_b32 m0, s68
	s_nop 0
	global_load_lds_dwordx4 v[240:241], off
	s_waitcnt vmcnt(8)
	s_waitcnt lgkmcnt(0)
	s_barrier
	s_setprio 1
	s_waitcnt lgkmcnt(0)
	v_mfma_f32_16x16x32_bf16 v[126:129], v[144:147], v[184:187], v[126:129]
	v_mfma_f32_16x16x32_bf16 v[126:129], v[156:159], v[188:191], v[126:129]
	v_mfma_f32_16x16x32_bf16 v[122:125], v[164:167], v[188:191], v[122:125]
	v_mfma_f32_16x16x32_bf16 v[122:125], v[160:163], v[184:187], v[122:125]
	v_mfma_f32_16x16x32_bf16 v[118:121], v[168:171], v[184:187], v[118:121]
	v_mfma_f32_16x16x32_bf16 v[118:121], v[172:175], v[188:191], v[118:121]
	v_mfma_f32_16x16x32_bf16 v[114:117], v[180:183], v[188:191], v[114:117]
	v_mfma_f32_16x16x32_bf16 v[114:117], v[176:179], v[184:187], v[114:117]
	v_mfma_f32_16x16x32_bf16 v[98:101], v[176:179], v[192:195], v[98:101]
	v_mfma_f32_16x16x32_bf16 v[98:101], v[180:183], v[196:199], v[98:101]
	v_mfma_f32_16x16x32_bf16 v[102:105], v[172:175], v[196:199], v[102:105]
	v_mfma_f32_16x16x32_bf16 v[102:105], v[168:171], v[192:195], v[102:105]
	v_mfma_f32_16x16x32_bf16 v[106:109], v[160:163], v[192:195], v[106:109]
	v_mfma_f32_16x16x32_bf16 v[106:109], v[164:167], v[196:199], v[106:109]
	v_mfma_f32_16x16x32_bf16 v[110:113], v[156:159], v[196:199], v[110:113]
	v_mfma_f32_16x16x32_bf16 v[110:113], v[144:147], v[192:195], v[110:113]
	s_setprio 0
	s_setprio 1
	v_mfma_f32_16x16x32_bf16 v[94:97], v[144:147], v[200:203], v[94:97]
	v_mfma_f32_16x16x32_bf16 v[94:97], v[156:159], v[204:207], v[94:97]
	v_mfma_f32_16x16x32_bf16 v[90:93], v[164:167], v[204:207], v[90:93]
	v_mfma_f32_16x16x32_bf16 v[90:93], v[160:163], v[200:203], v[90:93]
	v_mfma_f32_16x16x32_bf16 v[86:89], v[168:171], v[200:203], v[86:89]
	v_mfma_f32_16x16x32_bf16 v[86:89], v[172:175], v[204:207], v[86:89]
	v_mfma_f32_16x16x32_bf16 v[82:85], v[180:183], v[204:207], v[82:85]
	v_mfma_f32_16x16x32_bf16 v[82:85], v[176:179], v[200:203], v[82:85]
	v_mfma_f32_16x16x32_bf16 v[66:69], v[176:179], v[208:211], v[66:69]
	v_mfma_f32_16x16x32_bf16 v[66:69], v[180:183], v[232:235], v[66:69]
	v_mfma_f32_16x16x32_bf16 v[70:73], v[172:175], v[232:235], v[70:73]
	v_mfma_f32_16x16x32_bf16 v[70:73], v[168:171], v[208:211], v[70:73]
	v_mfma_f32_16x16x32_bf16 v[74:77], v[160:163], v[208:211], v[74:77]
	v_mfma_f32_16x16x32_bf16 v[74:77], v[164:167], v[232:235], v[74:77]
	v_mfma_f32_16x16x32_bf16 v[78:81], v[156:159], v[232:235], v[78:81]
	v_mfma_f32_16x16x32_bf16 v[78:81], v[144:147], v[208:211], v[78:81]
	s_setprio 0
	s_barrier
	s_add_i32 s22, s24, s16
	v_lshl_add_u64 v[148:149], v[148:149], 0, s[62:63]
	s_mov_b32 m0, s22
	ds_read_b128 v[184:187], v154 offset:49152
	ds_read_b128 v[188:191], v154 offset:50176
	ds_read_b128 v[192:195], v154 offset:51200
	ds_read_b128 v[196:199], v154 offset:52224
	ds_read_b128 v[200:203], v154 offset:53248
	ds_read_b128 v[204:207], v154 offset:54272
	ds_read_b128 v[208:211], v154 offset:55296
	ds_read_b128 v[232:235], v154 offset:56320
	global_load_lds_dwordx4 v[148:149], off
	s_add_i32 m0, s22, 0x2000
	s_add_u32 s22, s48, 0x80080
	v_lshl_add_u64 v[148:149], v[212:213], 0, s[62:63]
	s_addc_u32 s23, s49, 0
	s_add_i32 s24, s25, s16
	global_load_lds_dwordx4 v[148:149], off
	v_lshl_add_u64 v[148:149], s[22:23], 0, v[134:135]
	s_mov_b32 m0, s24
	s_nop 0
	global_load_lds_dwordx4 v[148:149], off
	v_lshl_add_u64 v[148:149], s[22:23], 0, v[130:131]
	s_add_i32 m0, s24, 0x2000
	s_nop 0
	global_load_lds_dwordx4 v[148:149], off
	v_lshl_add_u64 v[148:149], v[236:237], 0, s[62:63]
	s_mov_b32 m0, s69
	s_nop 0
	global_load_lds_dwordx4 v[148:149], off
	v_lshl_add_u64 v[148:149], v[238:239], 0, s[62:63]
	s_mov_b32 m0, s70
	s_nop 0
	global_load_lds_dwordx4 v[148:149], off
	s_waitcnt vmcnt(8)
	s_waitcnt lgkmcnt(0)
	s_barrier
	s_setprio 1
	s_waitcnt lgkmcnt(0)
	v_mfma_f32_16x16x32_bf16 v[62:65], v[144:147], v[184:187], v[62:65]
	v_mfma_f32_16x16x32_bf16 v[62:65], v[156:159], v[188:191], v[62:65]
	v_mfma_f32_16x16x32_bf16 v[58:61], v[164:167], v[188:191], v[58:61]
	v_mfma_f32_16x16x32_bf16 v[58:61], v[160:163], v[184:187], v[58:61]
	v_mfma_f32_16x16x32_bf16 v[54:57], v[168:171], v[184:187], v[54:57]
	v_mfma_f32_16x16x32_bf16 v[54:57], v[172:175], v[188:191], v[54:57]
	v_mfma_f32_16x16x32_bf16 v[50:53], v[180:183], v[188:191], v[50:53]
	v_mfma_f32_16x16x32_bf16 v[50:53], v[176:179], v[184:187], v[50:53]
	v_mfma_f32_16x16x32_bf16 v[34:37], v[176:179], v[192:195], v[34:37]
	v_mfma_f32_16x16x32_bf16 v[34:37], v[180:183], v[196:199], v[34:37]
	v_mfma_f32_16x16x32_bf16 v[38:41], v[172:175], v[196:199], v[38:41]
	v_mfma_f32_16x16x32_bf16 v[38:41], v[168:171], v[192:195], v[38:41]
	v_mfma_f32_16x16x32_bf16 v[42:45], v[160:163], v[192:195], v[42:45]
	v_mfma_f32_16x16x32_bf16 v[42:45], v[164:167], v[196:199], v[42:45]
	v_mfma_f32_16x16x32_bf16 v[46:49], v[156:159], v[196:199], v[46:49]
	v_mfma_f32_16x16x32_bf16 v[46:49], v[144:147], v[192:195], v[46:49]
	s_setprio 0
	s_setprio 1
	v_mfma_f32_16x16x32_bf16 v[30:33], v[144:147], v[200:203], v[30:33]
	v_mfma_f32_16x16x32_bf16 v[30:33], v[156:159], v[204:207], v[30:33]
	v_mfma_f32_16x16x32_bf16 v[26:29], v[164:167], v[204:207], v[26:29]
	v_mfma_f32_16x16x32_bf16 v[26:29], v[160:163], v[200:203], v[26:29]
	v_mfma_f32_16x16x32_bf16 v[22:25], v[168:171], v[200:203], v[22:25]
	v_mfma_f32_16x16x32_bf16 v[22:25], v[172:175], v[204:207], v[22:25]
	v_mfma_f32_16x16x32_bf16 v[18:21], v[180:183], v[204:207], v[18:21]
	v_mfma_f32_16x16x32_bf16 v[18:21], v[176:179], v[200:203], v[18:21]
	v_mfma_f32_16x16x32_bf16 v[2:5], v[176:179], v[208:211], v[2:5]
	v_mfma_f32_16x16x32_bf16 v[2:5], v[180:183], v[232:235], v[2:5]
	v_mfma_f32_16x16x32_bf16 v[6:9], v[172:175], v[232:235], v[6:9]
	v_mfma_f32_16x16x32_bf16 v[6:9], v[168:171], v[208:211], v[6:9]
	v_mfma_f32_16x16x32_bf16 v[10:13], v[160:163], v[208:211], v[10:13]
	v_mfma_f32_16x16x32_bf16 v[10:13], v[164:167], v[232:235], v[10:13]
	v_mfma_f32_16x16x32_bf16 v[14:17], v[156:159], v[232:235], v[14:17]
	v_mfma_f32_16x16x32_bf16 v[14:17], v[144:147], v[208:211], v[14:17]
	s_setprio 0
	s_barrier
	s_add_i32 s21, s21, 2
	s_add_u32 s46, s46, 0x100
	s_addc_u32 s47, s47, 0
	s_add_u32 s19, s19, 0x100
	s_addc_u32 s20, s20, 0
	s_cmp_gt_u32 s21, 29
	s_cbranch_scc0 .LBB0_340
	s_and_b64 vcc, exec, s[8:9]
	s_cbranch_vccz .LBB0_343
	s_barrier
